# static s_setprio 1 for waves 4-7 during the attention phases on top of the combined version
# baseline (speedup 1.0000x reference)
; #define LAS __attribute__((address_space(3)))
; __global__ void __launch_bounds__(512, 2) hybrid_fwd(Args a_unused) {
;     ...
;             lpre[2 * tid] = off; lpre[2 * tid + 1] = off + c0; if (tid == 511) lpre[1024] = off + c0 + c1;
;             __syncthreads(); }
;           const int T = (int)lpre[1024];
;           for (int u = bid; u < 1024 + T; u += G) {
;               if (u < 512) fox_unit((LAS char*)lds, u & 15, u >> 4, H, (const float*)(ws + WS_C), ctl, U, tid);
.LBB0_349:
	s_or_b64 exec, exec, s[0:1]
	s_waitcnt lgkmcnt(0)
	s_barrier
	v_readfirstlane_b32 s101, v218
	s_cmp_lt_u32 s101, 0x100
	s_cbranch_scc1 .Lp3_noprio
	s_setprio 1

; __global__ void __launch_bounds__(512, 2) hybrid_fwd(Args a_unused) {
	.amdhsa_kernel _Z10hybrid_fwd4Args
		.amdhsa_group_segment_fixed_size 0
		.amdhsa_private_segment_fixed_size 0
		.amdhsa_kernarg_size 352
		.amdhsa_user_sgpr_count 2
		.amdhsa_user_sgpr_dispatch_ptr 0
		.amdhsa_user_sgpr_queue_ptr 0
		.amdhsa_user_sgpr_kernarg_segment_ptr 1
		.amdhsa_user_sgpr_dispatch_id 0
		.amdhsa_user_sgpr_kernarg_preload_length 0
		.amdhsa_user_sgpr_kernarg_preload_offset 0
		.amdhsa_user_sgpr_private_segment_size 0
		.amdhsa_uses_dynamic_stack 0
		.amdhsa_enable_private_segment 0
		.amdhsa_system_sgpr_workgroup_id_x 1
		.amdhsa_system_sgpr_workgroup_id_y 0
		.amdhsa_system_sgpr_workgroup_id_z 0
		.amdhsa_system_sgpr_workgroup_info 0
		.amdhsa_system_vgpr_workitem_id 2
		.amdhsa_next_free_vgpr 255
		.amdhsa_next_free_sgpr 102
		.amdhsa_accum_offset 256
		.amdhsa_reserve_vcc 1
		.amdhsa_float_round_mode_32 0
		.amdhsa_float_round_mode_16_64 0
		.amdhsa_float_denorm_mode_32 3
		.amdhsa_float_denorm_mode_16_64 3
		.amdhsa_dx10_clamp 1
		.amdhsa_ieee_mode 1
		.amdhsa_fp16_overflow 0
		.amdhsa_tg_split 0
		.amdhsa_exception_fp_ieee_invalid_op 0
		.amdhsa_exception_fp_denorm_src 0
		.amdhsa_exception_fp_ieee_div_zero 0
		.amdhsa_exception_fp_ieee_overflow 0
		.amdhsa_exception_fp_ieee_underflow 0
		.amdhsa_exception_fp_ieee_inexact 0
		.amdhsa_exception_int_div_zero 0
	.end_amdhsa_kernel

; __global__ void __launch_bounds__(512, 2) hybrid_fwd(Args a_unused) {
amdhsa.kernels:
  - .agpr_count:     0
    .args:
      - .offset:         0
        .size:           96
        .value_kind:     by_value
      - .offset:         96
        .size:           4
        .value_kind:     hidden_block_count_x
      - .offset:         100
        .size:           4
        .value_kind:     hidden_block_count_y
      - .offset:         104
        .size:           4
        .value_kind:     hidden_block_count_z
      - .offset:         108
        .size:           2
        .value_kind:     hidden_group_size_x
      - .offset:         110
        .size:           2
        .value_kind:     hidden_group_size_y
      - .offset:         112
        .size:           2
        .value_kind:     hidden_group_size_z
      - .offset:         114
        .size:           2
        .value_kind:     hidden_remainder_x
      - .offset:         116
        .size:           2
        .value_kind:     hidden_remainder_y
      - .offset:         118
        .size:           2
        .value_kind:     hidden_remainder_z
      - .offset:         136
        .size:           8
        .value_kind:     hidden_global_offset_x
      - .offset:         144
        .size:           8
        .value_kind:     hidden_global_offset_y
      - .offset:         152
        .size:           8
        .value_kind:     hidden_global_offset_z
      - .offset:         160
        .size:           2
        .value_kind:     hidden_grid_dims
      - .offset:         184
        .size:           8
        .value_kind:     hidden_multigrid_sync_arg
      - .offset:         216
        .size:           4
        .value_kind:     hidden_dynamic_lds_size
    .group_segment_fixed_size: 0
    .kernarg_segment_align: 8
    .kernarg_segment_size: 352
    .language:       OpenCL C
    .language_version:
      - 2
      - 0
    .max_flat_workgroup_size: 512
    .name:           _Z10hybrid_fwd4Args
    .private_segment_fixed_size: 0
    .sgpr_count:     108
    .sgpr_spill_count: 143
    .symbol:         _Z10hybrid_fwd4Args.kd
    .uniform_work_group_size: 1
    .uses_dynamic_stack: false
    .vgpr_count:     255
    .vgpr_spill_count: 0
    .wavefront_size: 64
